# speedup vs baseline: 1.0004x; 1.0004x over previous
; __device__ __forceinline__ float lo_bf(unsigned u) { return __uint_as_float(u << 16); }
; __device__ __forceinline__ float hi_bf(unsigned u) { return __uint_as_float(u & 0xffff0000u); }
; __device__ __forceinline__ int get_tid() { return get_tid512() & 255; }
; __device__ __forceinline__ void cmlp_item(const Params& p, int j, int rt, int g, const u16* __restrict__ ZB, u16* sVT) {
;   const int tid = get_tid(), lane = tid & 63, wave = tid >> 6, fr = lane & 15, fq = lane >> 4;
;   const int m0 = rt * 128;
;   __syncthreads();
;   {
;     const int q = tid >> 1, half = tid & 1;
;     const u16* src = ZB + (size_t)(m0 + q) * 1024 + 512 + g * 128 + half * 64;
;     uint4 raw[8];
; #pragma unroll
;     for (int i = 0; i < 8; ++i) raw[i] = *(const uint4*)(src + i * 8);
;     float ss = 0.f;
; #pragma unroll
;     for (int i = 0; i < 8; ++i) {
;       unsigned w[4] = {raw[i].x, raw[i].y, raw[i].z, raw[i].w};
; #pragma unroll
;       for (int k = 0; k < 4; ++k) { float a = lo_bf(w[k]), b = hi_bf(w[k]); ss += a * a + b * b; }
;     }
;     ss += __shfl_xor(ss, 1);
;     const float rstd = rsqrtf(ss * (1.f / 128.f) + EPSV);
.LBB0_1553:
	v_mov_b32_e32 v38, v206
	s_and_b32 s9, s1, 0xffffff80
	v_bfe_u32 v0, v38, 1, 7
	v_or_b32_e32 v2, s9, v0
	v_ashrrev_i32_e32 v3, 31, v2
	s_and_b32 s10, s0, 3
	v_lshlrev_b64 v[2:3], 11, v[2:3]
	v_lshlrev_b32_e32 v0, 6, v38
	v_lshl_add_u64 v[2:3], s[92:93], 0, v[2:3]
	s_lshl_b32 s34, s10, 8
	v_and_b32_e32 v39, 64, v0
	v_lshl_add_u64 v[2:3], v[2:3], 0, s[34:35]
	v_lshlrev_b32_e32 v0, 1, v39
	v_lshl_add_u64 v[30:31], v[2:3], 0, v[0:1]
	s_waitcnt lgkmcnt(0)
	s_barrier
	global_load_dwordx4 v[2:5], v[30:31], off offset:1072
	global_load_dwordx4 v[6:9], v[30:31], off offset:1056
	global_load_dwordx4 v[10:13], v[30:31], off offset:1040
	global_load_dwordx4 v[14:17], v[30:31], off offset:1024
	global_load_dwordx4 v[18:21], v[30:31], off offset:1104
	global_load_dwordx4 v[22:25], v[30:31], off offset:1088
	global_load_dwordx4 v[26:29], v[30:31], off offset:1136
	s_nop 0
	global_load_dwordx4 v[30:33], v[30:31], off offset:1120
	s_lshl_b32 s6, s10, 9
	s_add_u32 s6, s14, s6
	s_addc_u32 s7, s15, 0
	v_lshlrev_b32_e32 v87, 2, v39
	s_or_b32 s10, s10, s16
	v_and_b32_e32 v67, 15, v38
	v_bfe_u32 v66, v38, 6, 2
	s_waitcnt vmcnt(7)
	v_and_b32_e32 v64, 0xffff0000, v2
	s_waitcnt vmcnt(6)
	v_and_b32_e32 v56, 0xffff0000, v6
	s_waitcnt vmcnt(5)
	v_and_b32_e32 v48, 0xffff0000, v10
	s_waitcnt vmcnt(4)
	v_and_b32_e32 v40, 0xffff0000, v14
	v_and_b32_e32 v42, 0xffff0000, v15
	v_lshlrev_b32_e32 v0, 16, v14
	v_mul_f32_e32 v14, v40, v40
	v_lshlrev_b32_e32 v41, 16, v15
	v_mul_f32_e32 v15, v42, v42
	v_fmac_f32_e32 v14, v0, v0
	v_fmac_f32_e32 v15, v41, v41
	v_and_b32_e32 v44, 0xffff0000, v16
	v_add_f32_e32 v14, v14, v15
	v_lshlrev_b32_e32 v43, 16, v16
	v_mul_f32_e32 v15, v44, v44
	v_fmac_f32_e32 v15, v43, v43
	v_and_b32_e32 v46, 0xffff0000, v17
	v_add_f32_e32 v14, v14, v15
	v_lshlrev_b32_e32 v45, 16, v17
	v_mul_f32_e32 v15, v46, v46
	v_fmac_f32_e32 v15, v45, v45
	v_lshlrev_b32_e32 v47, 16, v10
	v_mul_f32_e32 v10, v48, v48
	v_and_b32_e32 v50, 0xffff0000, v11
	v_add_f32_e32 v14, v14, v15
	v_fmac_f32_e32 v10, v47, v47
	v_lshlrev_b32_e32 v49, 16, v11
	v_mul_f32_e32 v11, v50, v50
	v_add_f32_e32 v10, v14, v10
	v_fmac_f32_e32 v11, v49, v49
	v_and_b32_e32 v52, 0xffff0000, v12
	v_add_f32_e32 v10, v10, v11
	v_lshlrev_b32_e32 v51, 16, v12
	v_mul_f32_e32 v11, v52, v52
	v_fmac_f32_e32 v11, v51, v51
	v_and_b32_e32 v54, 0xffff0000, v13
	v_add_f32_e32 v10, v10, v11
	v_lshlrev_b32_e32 v53, 16, v13
	v_mul_f32_e32 v11, v54, v54
	v_fmac_f32_e32 v11, v53, v53
	v_lshlrev_b32_e32 v55, 16, v6
	v_mul_f32_e32 v6, v56, v56
	v_and_b32_e32 v58, 0xffff0000, v7
	v_add_f32_e32 v10, v10, v11
	v_fmac_f32_e32 v6, v55, v55
	v_lshlrev_b32_e32 v57, 16, v7
	v_mul_f32_e32 v7, v58, v58
	v_add_f32_e32 v6, v10, v6
	v_fmac_f32_e32 v7, v57, v57
	v_and_b32_e32 v60, 0xffff0000, v8
	v_add_f32_e32 v6, v6, v7
	v_lshlrev_b32_e32 v59, 16, v8
	v_mul_f32_e32 v7, v60, v60
	v_fmac_f32_e32 v7, v59, v59
	v_and_b32_e32 v62, 0xffff0000, v9
	v_add_f32_e32 v6, v6, v7
	v_lshlrev_b32_e32 v61, 16, v9
	v_mul_f32_e32 v7, v62, v62
	v_fmac_f32_e32 v7, v61, v61
	v_lshlrev_b32_e32 v63, 16, v2
	v_mul_f32_e32 v2, v64, v64
	v_and_b32_e32 v68, 0xffff0000, v3
	v_add_f32_e32 v6, v6, v7
	v_fmac_f32_e32 v2, v63, v63
	v_lshlrev_b32_e32 v65, 16, v3
	v_mul_f32_e32 v3, v68, v68
	v_add_f32_e32 v2, v6, v2
	v_fmac_f32_e32 v3, v65, v65
	v_and_b32_e32 v70, 0xffff0000, v4
	v_add_f32_e32 v2, v2, v3
	v_lshlrev_b32_e32 v69, 16, v4
	v_mul_f32_e32 v3, v70, v70
	v_fmac_f32_e32 v3, v69, v69
	v_and_b32_e32 v73, 0xffff0000, v5
	v_add_f32_e32 v2, v2, v3
	v_lshlrev_b32_e32 v72, 16, v5
	v_mul_f32_e32 v3, v73, v73
	v_fmac_f32_e32 v3, v72, v72
	s_waitcnt vmcnt(2)
	v_and_b32_e32 v75, 0xffff0000, v22
	v_add_f32_e32 v2, v2, v3
	v_lshlrev_b32_e32 v74, 16, v22
	v_mul_f32_e32 v3, v75, v75
	v_fmac_f32_e32 v3, v74, v74
	v_and_b32_e32 v77, 0xffff0000, v23
	v_add_f32_e32 v2, v2, v3
	v_lshlrev_b32_e32 v76, 16, v23
	v_mul_f32_e32 v3, v77, v77
	v_fmac_f32_e32 v3, v76, v76
	v_and_b32_e32 v79, 0xffff0000, v24
	v_add_f32_e32 v2, v2, v3
	v_lshlrev_b32_e32 v78, 16, v24
	v_mul_f32_e32 v3, v79, v79
	v_fmac_f32_e32 v3, v78, v78
	v_and_b32_e32 v81, 0xffff0000, v25
	v_add_f32_e32 v2, v2, v3
	v_lshlrev_b32_e32 v80, 16, v25
	v_mul_f32_e32 v3, v81, v81
	v_fmac_f32_e32 v3, v80, v80
	v_and_b32_e32 v83, 0xffff0000, v18
	v_add_f32_e32 v2, v2, v3
	v_lshlrev_b32_e32 v82, 16, v18
	v_mul_f32_e32 v3, v83, v83
	v_fmac_f32_e32 v3, v82, v82
	v_and_b32_e32 v85, 0xffff0000, v19
	v_add_f32_e32 v2, v2, v3
	v_lshlrev_b32_e32 v84, 16, v19
	v_mul_f32_e32 v3, v85, v85
	v_fmac_f32_e32 v3, v84, v84
	v_and_b32_e32 v19, 0xffff0000, v21
	v_and_b32_e32 v18, 0xffff0000, v20
	v_add_f32_e32 v4, v2, v3
	v_lshlrev_b32_e32 v37, 16, v21
	v_lshlrev_b32_e32 v36, 16, v20
	v_pk_mul_f32 v[2:3], v[18:19], v[18:19]
	s_waitcnt vmcnt(0)
	v_and_b32_e32 v15, 0xffff0000, v31
	v_pk_fma_f32 v[2:3], v[36:37], v[36:37], v[2:3]
	v_and_b32_e32 v14, 0xffff0000, v30
	v_add_f32_e32 v2, v4, v2
	v_add_f32_e32 v4, v2, v3
	v_lshlrev_b32_e32 v17, 16, v31
	v_lshlrev_b32_e32 v16, 16, v30
	v_pk_mul_f32 v[2:3], v[14:15], v[14:15]
	v_and_b32_e32 v11, 0xffff0000, v33
	v_pk_fma_f32 v[2:3], v[16:17], v[16:17], v[2:3]
	v_and_b32_e32 v10, 0xffff0000, v32
	v_add_f32_e32 v2, v4, v2
	v_add_f32_e32 v4, v2, v3
	v_lshlrev_b32_e32 v13, 16, v33
	v_lshlrev_b32_e32 v12, 16, v32
	v_pk_mul_f32 v[2:3], v[10:11], v[10:11]
	v_and_b32_e32 v7, 0xffff0000, v27
	v_pk_fma_f32 v[2:3], v[12:13], v[12:13], v[2:3]
	v_and_b32_e32 v6, 0xffff0000, v26
	v_add_f32_e32 v2, v4, v2
	v_add_f32_e32 v4, v2, v3
	v_lshlrev_b32_e32 v9, 16, v27
	v_lshlrev_b32_e32 v8, 16, v26
	v_pk_mul_f32 v[2:3], v[6:7], v[6:7]
	v_lshlrev_b32_e32 v5, 16, v29
	v_pk_fma_f32 v[2:3], v[8:9], v[8:9], v[2:3]
	s_nop 0
	v_add_f32_e32 v2, v4, v2
	v_add_f32_e32 v22, v2, v3
	v_and_b32_e32 v3, 0xffff0000, v29
	v_and_b32_e32 v2, 0xffff0000, v28
	v_lshlrev_b32_e32 v4, 16, v28
	v_pk_mul_f32 v[20:21], v[2:3], v[2:3]
	s_nop 0
	v_pk_fma_f32 v[20:21], v[4:5], v[4:5], v[20:21]
	s_nop 0
	v_add_f32_e32 v20, v22, v20
	v_add_f32_e32 v20, v20, v21
	ds_bpermute_b32 v21, v71, v20
	s_waitcnt lgkmcnt(0)
; __device__ __forceinline__ float lo_bf(unsigned u) { return __uint_as_float(u << 16); }
; __device__ __forceinline__ float hi_bf(unsigned u) { return __uint_as_float(u & 0xffff0000u); }
; __device__ __forceinline__ void cmlp_item(const Params& p, int j, int rt, int g, const u16* __restrict__ ZB, u16* sVT) {
;     ...
;     const float rstd = rsqrtf(ss * (1.f / 128.f) + EPSV);
;     const float* vn = p.cmlp_v_norm + j * 512 + g * 128 + half * 64;
; #pragma unroll
;     for (int i = 0; i < 8; ++i) {
;       unsigned w[4] = {raw[i].x, raw[i].y, raw[i].z, raw[i].w};
; #pragma unroll
;       for (int k = 0; k < 4; ++k) {
;         int d = i * 8 + k * 2;
;         sVT[(half * 64 + d) * 136 + q] = f2bf(lo_bf(w[k]) * rstd * vn[d]);
;         sVT[(half * 64 + d + 1) * 136 + q] = f2bf(hi_bf(w[k]) * rstd * vn[d + 1]);
;       }
;     }
	v_add_f32_e32 v20, v20, v21
	v_fmamk_f32 v20, v20, 0x3c000000, v252
	v_cmp_gt_f32_e32 vcc, s90, v20
	v_mul_f32_e32 v21, 0x4b800000, v20
	s_nop 0
	v_cndmask_b32_e32 v20, v20, v21, vcc
	v_rsq_f32_e32 v20, v20
	s_nop 0
	v_mul_f32_e32 v21, 0x45800000, v20
	v_cndmask_b32_e32 v86, v20, v21, vcc
	global_load_dwordx4 v[112:115], v87, s[6:7]
	global_load_dwordx4 v[116:119], v87, s[6:7] offset:16
	global_load_dwordx4 v[120:123], v87, s[6:7] offset:32
	global_load_dwordx4 v[124:127], v87, s[6:7] offset:48
	global_load_dwordx4 v[128:131], v87, s[6:7] offset:64
	global_load_dwordx4 v[132:135], v87, s[6:7] offset:80
	global_load_dwordx4 v[136:139], v87, s[6:7] offset:96
	global_load_dwordx4 v[140:143], v87, s[6:7] offset:112
	global_load_dwordx4 v[144:147], v87, s[6:7] offset:128
	global_load_dwordx4 v[148:151], v87, s[6:7] offset:144
	global_load_dwordx4 v[152:155], v87, s[6:7] offset:160
	global_load_dwordx4 v[156:159], v87, s[6:7] offset:176
	global_load_dwordx4 v[160:163], v87, s[6:7] offset:192
	global_load_dwordx4 v[164:167], v87, s[6:7] offset:208
	global_load_dwordx4 v[168:171], v87, s[6:7] offset:224
	global_load_dwordx4 v[172:175], v87, s[6:7] offset:240
	v_mul_f32_e32 v0, v86, v0
	s_waitcnt vmcnt(0)
	v_mov_b32_e32 v20, v124
	v_mov_b32_e32 v21, v125
	v_mov_b32_e32 v22, v126
	v_mov_b32_e32 v23, v127
	v_mov_b32_e32 v24, v120
	v_mov_b32_e32 v25, v121
	v_mov_b32_e32 v26, v122
	v_mov_b32_e32 v27, v123
	v_mov_b32_e32 v28, v116
	v_mov_b32_e32 v29, v117
	v_mov_b32_e32 v30, v118
	v_mov_b32_e32 v31, v119
	v_mov_b32_e32 v32, v112
	v_mov_b32_e32 v33, v113
	v_mov_b32_e32 v34, v114
	v_mov_b32_e32 v35, v115
	v_mul_f32_e32 v0, v32, v0
	v_mul_u32_u24_e32 v32, 0x88, v39
	v_lshlrev_b32_e32 v32, 1, v32
	v_and_b32_e32 v39, 0xfe, v38
	v_cvt_pk_bf16_f32 v0, v0, s0
	v_add3_u32 v88, s58, v32, v39
	ds_write_b16 v88, v0
	v_mul_f32_e32 v0, v86, v40
	v_mul_f32_e32 v0, v33, v0
	v_cvt_pk_bf16_f32 v0, v0, s0
	v_add3_u32 v39, s58, v39, v32
	ds_write_b16 v39, v0 offset:272
	v_mul_f32_e32 v0, v86, v41
	v_mul_f32_e32 v0, v34, v0
	v_cvt_pk_bf16_f32 v0, v0, s0
	ds_write_b16 v88, v0 offset:544
	v_mul_f32_e32 v0, v86, v42
	v_mul_f32_e32 v0, v35, v0
	v_cvt_pk_bf16_f32 v0, v0, s0
	ds_write_b16 v39, v0 offset:816
	v_mul_f32_e32 v0, v86, v43
	v_mul_f32_e32 v0, v28, v0
	v_cvt_pk_bf16_f32 v0, v0, s0
	ds_write_b16 v88, v0 offset:1088
	v_mul_f32_e32 v0, v86, v44
	v_mul_f32_e32 v0, v0, v29
	v_cvt_pk_bf16_f32 v0, v0, s0
	ds_write_b16 v39, v0 offset:1360
	v_mul_f32_e32 v0, v86, v45
	v_mul_f32_e32 v0, v0, v30
	v_cvt_pk_bf16_f32 v0, v0, s0
	ds_write_b16 v88, v0 offset:1632
	v_mul_f32_e32 v0, v86, v46
	v_mul_f32_e32 v0, v0, v31
	v_cvt_pk_bf16_f32 v0, v0, s0
	ds_write_b16 v39, v0 offset:1904
	v_mul_f32_e32 v0, v86, v47
	v_mul_f32_e32 v0, v0, v24
	v_cvt_pk_bf16_f32 v0, v0, s0
	ds_write_b16 v88, v0 offset:2176
	v_mul_f32_e32 v0, v86, v48
	v_mul_f32_e32 v0, v0, v25
	v_cvt_pk_bf16_f32 v0, v0, s0
	ds_write_b16 v39, v0 offset:2448
	v_mul_f32_e32 v0, v86, v49
	v_mul_f32_e32 v0, v0, v26
	v_cvt_pk_bf16_f32 v0, v0, s0
	ds_write_b16 v88, v0 offset:2720
	v_mul_f32_e32 v0, v86, v50
	v_mul_f32_e32 v0, v0, v27
	v_cvt_pk_bf16_f32 v0, v0, s0
	ds_write_b16 v39, v0 offset:2992
	v_mul_f32_e32 v0, v86, v51
	v_mul_f32_e32 v0, v0, v20
	v_cvt_pk_bf16_f32 v0, v0, s0
	ds_write_b16 v88, v0 offset:3264
	v_mul_f32_e32 v0, v86, v52
	v_mul_f32_e32 v0, v0, v21
	v_cvt_pk_bf16_f32 v0, v0, s0
	ds_write_b16 v39, v0 offset:3536
	v_mul_f32_e32 v0, v86, v53
	v_mul_f32_e32 v0, v0, v22
	v_cvt_pk_bf16_f32 v0, v0, s0
	ds_write_b16 v88, v0 offset:3808
	v_mul_f32_e32 v0, v86, v54
	v_mul_f32_e32 v0, v0, v23
	v_cvt_pk_bf16_f32 v0, v0, s0
	ds_write_b16 v39, v0 offset:4080
	v_mul_f32_e32 v0, v86, v55
	s_waitcnt vmcnt(0)
	v_mov_b32_e32 v20, v140
	v_mov_b32_e32 v21, v141
	v_mov_b32_e32 v22, v142
	v_mov_b32_e32 v23, v143
	v_mov_b32_e32 v24, v136
	v_mov_b32_e32 v25, v137
	v_mov_b32_e32 v26, v138
	v_mov_b32_e32 v27, v139
	v_mov_b32_e32 v28, v132
	v_mov_b32_e32 v29, v133
	v_mov_b32_e32 v30, v134
	v_mov_b32_e32 v31, v135
	v_mov_b32_e32 v32, v128
	v_mov_b32_e32 v33, v129
	v_mov_b32_e32 v34, v130
	v_mov_b32_e32 v35, v131
	v_mul_f32_e32 v0, v0, v32
	v_cvt_pk_bf16_f32 v0, v0, s0
	ds_write_b16 v88, v0 offset:4352
	v_mul_f32_e32 v0, v86, v56
	v_mul_f32_e32 v0, v0, v33
	v_cvt_pk_bf16_f32 v0, v0, s0
	ds_write_b16 v39, v0 offset:4624
	v_mul_f32_e32 v0, v86, v57
	v_mul_f32_e32 v0, v0, v34
	v_cvt_pk_bf16_f32 v0, v0, s0
	ds_write_b16 v88, v0 offset:4896
	v_mul_f32_e32 v0, v86, v58
	v_mul_f32_e32 v0, v0, v35
	v_cvt_pk_bf16_f32 v0, v0, s0
	ds_write_b16 v39, v0 offset:5168
	v_mul_f32_e32 v0, v86, v59
	v_mul_f32_e32 v0, v0, v28
	v_cvt_pk_bf16_f32 v0, v0, s0
	ds_write_b16 v88, v0 offset:5440
	v_mul_f32_e32 v0, v86, v60
	v_mul_f32_e32 v0, v0, v29
	v_cvt_pk_bf16_f32 v0, v0, s0
	ds_write_b16 v39, v0 offset:5712
	v_mul_f32_e32 v0, v86, v61
	v_mul_f32_e32 v0, v0, v30
	v_cvt_pk_bf16_f32 v0, v0, s0
	ds_write_b16 v88, v0 offset:5984
	v_mul_f32_e32 v0, v86, v62
	v_mul_f32_e32 v0, v0, v31
	v_cvt_pk_bf16_f32 v0, v0, s0
	ds_write_b16 v39, v0 offset:6256
	v_mul_f32_e32 v0, v86, v63
	v_mul_f32_e32 v0, v0, v24
	v_cvt_pk_bf16_f32 v0, v0, s0
	ds_write_b16 v88, v0 offset:6528
	v_mul_f32_e32 v0, v86, v64
	v_mul_f32_e32 v0, v0, v25
	v_cvt_pk_bf16_f32 v0, v0, s0
	ds_write_b16 v39, v0 offset:6800
	v_mul_f32_e32 v0, v86, v65
	v_mul_f32_e32 v0, v0, v26
	v_cvt_pk_bf16_f32 v0, v0, s0
	ds_write_b16 v88, v0 offset:7072
	v_mul_f32_e32 v0, v86, v68
	v_mul_f32_e32 v0, v0, v27
	v_cvt_pk_bf16_f32 v0, v0, s0
	ds_write_b16 v39, v0 offset:7344
	v_mul_f32_e32 v0, v86, v69
	v_mul_f32_e32 v0, v0, v20
	v_cvt_pk_bf16_f32 v0, v0, s0
	ds_write_b16 v88, v0 offset:7616
	v_mul_f32_e32 v0, v86, v70
	v_mul_f32_e32 v0, v0, v21
	v_cvt_pk_bf16_f32 v0, v0, s0
	ds_write_b16 v39, v0 offset:7888
	v_mul_f32_e32 v0, v86, v72
	v_mul_f32_e32 v0, v0, v22
	v_cvt_pk_bf16_f32 v0, v0, s0
	ds_write_b16 v88, v0 offset:8160
	v_mul_f32_e32 v0, v86, v73
	v_mul_f32_e32 v0, v0, v23
	v_cvt_pk_bf16_f32 v0, v0, s0
	ds_write_b16 v39, v0 offset:8432
	v_mul_f32_e32 v0, v86, v74
	s_waitcnt vmcnt(0)
; __device__ __forceinline__ float lo_bf(unsigned u) { return __uint_as_float(u << 16); }
; __device__ __forceinline__ float hi_bf(unsigned u) { return __uint_as_float(u & 0xffff0000u); }
; __device__ __forceinline__ void cmlp_item(const Params& p, int j, int rt, int g, const u16* __restrict__ ZB, u16* sVT) {
;     ...
;     const float* vn = p.cmlp_v_norm + j * 512 + g * 128 + half * 64;
; #pragma unroll
;     for (int i = 0; i < 8; ++i) {
;       unsigned w[4] = {raw[i].x, raw[i].y, raw[i].z, raw[i].w};
; #pragma unroll
;       for (int k = 0; k < 4; ++k) {
;         int d = i * 8 + k * 2;
;         sVT[(half * 64 + d) * 136 + q] = f2bf(lo_bf(w[k]) * rstd * vn[d]);
;         sVT[(half * 64 + d + 1) * 136 + q] = f2bf(hi_bf(w[k]) * rstd * vn[d + 1]);
;       }
;     }
;   }
;   __syncthreads();
	v_mov_b32_e32 v20, v156
	v_mov_b32_e32 v21, v157
	v_mov_b32_e32 v22, v158
	v_mov_b32_e32 v23, v159
	v_mov_b32_e32 v24, v152
	v_mov_b32_e32 v25, v153
	v_mov_b32_e32 v26, v154
	v_mov_b32_e32 v27, v155
	v_mov_b32_e32 v28, v148
	v_mov_b32_e32 v29, v149
	v_mov_b32_e32 v30, v150
	v_mov_b32_e32 v31, v151
	v_mov_b32_e32 v32, v144
	v_mov_b32_e32 v33, v145
	v_mov_b32_e32 v34, v146
	v_mov_b32_e32 v35, v147
	v_mul_f32_e32 v0, v0, v32
	v_cvt_pk_bf16_f32 v0, v0, s0
	ds_write_b16 v88, v0 offset:8704
	v_mul_f32_e32 v0, v86, v75
	v_mul_f32_e32 v0, v0, v33
	v_cvt_pk_bf16_f32 v0, v0, s0
	ds_write_b16 v39, v0 offset:8976
	v_mul_f32_e32 v0, v86, v76
	v_mul_f32_e32 v0, v0, v34
	v_cvt_pk_bf16_f32 v0, v0, s0
	ds_write_b16 v88, v0 offset:9248
	v_mul_f32_e32 v0, v86, v77
	v_mul_f32_e32 v0, v0, v35
	v_cvt_pk_bf16_f32 v0, v0, s0
	ds_write_b16 v39, v0 offset:9520
	v_mul_f32_e32 v0, v86, v78
	v_mul_f32_e32 v0, v0, v28
	v_cvt_pk_bf16_f32 v0, v0, s0
	ds_write_b16 v88, v0 offset:9792
	v_mul_f32_e32 v0, v86, v79
	v_mul_f32_e32 v0, v0, v29
	v_cvt_pk_bf16_f32 v0, v0, s0
	ds_write_b16 v39, v0 offset:10064
	v_mul_f32_e32 v0, v86, v80
	v_mul_f32_e32 v0, v0, v30
	v_cvt_pk_bf16_f32 v0, v0, s0
	ds_write_b16 v88, v0 offset:10336
	v_mul_f32_e32 v0, v86, v81
	v_mul_f32_e32 v0, v0, v31
	v_cvt_pk_bf16_f32 v0, v0, s0
	ds_write_b16 v39, v0 offset:10608
	v_mul_f32_e32 v0, v86, v82
	v_mul_f32_e32 v0, v0, v24
	v_cvt_pk_bf16_f32 v0, v0, s0
	ds_write_b16 v88, v0 offset:10880
	v_mul_f32_e32 v0, v86, v83
	v_mul_f32_e32 v0, v0, v25
	v_cvt_pk_bf16_f32 v0, v0, s0
	ds_write_b16 v39, v0 offset:11152
	v_mul_f32_e32 v0, v86, v84
	v_mul_f32_e32 v0, v0, v26
	v_cvt_pk_bf16_f32 v0, v0, s0
	ds_write_b16 v88, v0 offset:11424
	v_mul_f32_e32 v0, v86, v85
	v_mul_f32_e32 v0, v0, v27
	v_cvt_pk_bf16_f32 v0, v0, s0
	ds_write_b16 v39, v0 offset:11696
	v_mul_f32_e32 v0, v86, v36
	v_mul_f32_e32 v0, v0, v20
	v_cvt_pk_bf16_f32 v0, v0, s0
	ds_write_b16 v88, v0 offset:11968
	v_mul_f32_e32 v0, v86, v18
	v_mul_f32_e32 v0, v0, v21
	v_cvt_pk_bf16_f32 v0, v0, s0
	ds_write_b16 v39, v0 offset:12240
	v_mul_f32_e32 v0, v86, v37
	v_mul_f32_e32 v0, v0, v22
	v_cvt_pk_bf16_f32 v0, v0, s0
	ds_write_b16 v88, v0 offset:12512
	v_mul_f32_e32 v0, v86, v19
	v_mul_f32_e32 v0, v0, v23
	v_cvt_pk_bf16_f32 v0, v0, s0
	ds_write_b16 v39, v0 offset:12784
	v_mul_f32_e32 v0, v86, v16
	s_lshl_b32 s6, s10, 16
	s_add_u32 s6, s46, s6
	s_addc_u32 s7, s47, 0
	s_waitcnt vmcnt(0)
	v_mov_b32_e32 v18, v172
	v_mov_b32_e32 v19, v173
	v_mov_b32_e32 v20, v174
	v_mov_b32_e32 v21, v175
	v_mov_b32_e32 v22, v168
	v_mov_b32_e32 v23, v169
	v_mov_b32_e32 v24, v170
	v_mov_b32_e32 v25, v171
	v_mov_b32_e32 v26, v164
	v_mov_b32_e32 v27, v165
	v_mov_b32_e32 v28, v166
	v_mov_b32_e32 v29, v167
	v_mov_b32_e32 v30, v160
	v_mov_b32_e32 v31, v161
	v_mov_b32_e32 v32, v162
	v_mov_b32_e32 v33, v163
	v_mul_f32_e32 v0, v0, v30
	v_cvt_pk_bf16_f32 v0, v0, s0
	ds_write_b16 v88, v0 offset:13056
	v_mul_f32_e32 v0, v86, v14
	v_mul_f32_e32 v0, v0, v31
	v_cvt_pk_bf16_f32 v0, v0, s0
	ds_write_b16 v39, v0 offset:13328
	v_mul_f32_e32 v0, v86, v17
	v_mul_f32_e32 v0, v0, v32
	v_cvt_pk_bf16_f32 v0, v0, s0
	ds_write_b16 v88, v0 offset:13600
	v_mul_f32_e32 v0, v86, v15
	v_mul_f32_e32 v0, v0, v33
	v_cvt_pk_bf16_f32 v0, v0, s0
	ds_write_b16 v39, v0 offset:13872
	v_mul_f32_e32 v0, v86, v12
	v_mul_f32_e32 v0, v0, v26
	v_cvt_pk_bf16_f32 v0, v0, s0
	ds_write_b16 v88, v0 offset:14144
	v_mul_f32_e32 v0, v86, v10
	v_mul_f32_e32 v0, v0, v27
	v_cvt_pk_bf16_f32 v0, v0, s0
	ds_write_b16 v39, v0 offset:14416
	v_mul_f32_e32 v0, v86, v13
	v_mul_f32_e32 v0, v0, v28
	v_cvt_pk_bf16_f32 v0, v0, s0
	ds_write_b16 v88, v0 offset:14688
	v_mul_f32_e32 v0, v86, v11
	v_mul_f32_e32 v0, v0, v29
	v_cvt_pk_bf16_f32 v0, v0, s0
	ds_write_b16 v39, v0 offset:14960
	v_mul_f32_e32 v0, v86, v8
	v_mul_f32_e32 v0, v0, v22
	v_cvt_pk_bf16_f32 v0, v0, s0
	ds_write_b16 v88, v0 offset:15232
	v_mul_f32_e32 v0, v86, v6
	v_mul_f32_e32 v0, v0, v23
	v_cvt_pk_bf16_f32 v0, v0, s0
	ds_write_b16 v39, v0 offset:15504
	v_mul_f32_e32 v0, v86, v9
	v_mul_f32_e32 v0, v0, v24
	v_cvt_pk_bf16_f32 v0, v0, s0
	ds_write_b16 v88, v0 offset:15776
	v_mul_f32_e32 v0, v86, v7
	v_mul_f32_e32 v0, v0, v25
	v_cvt_pk_bf16_f32 v0, v0, s0
	ds_write_b16 v39, v0 offset:16048
	v_mul_f32_e32 v0, v86, v4
	v_mul_f32_e32 v0, v0, v18
	v_cvt_pk_bf16_f32 v0, v0, s0
	ds_write_b16 v88, v0 offset:16320
	v_mul_f32_e32 v0, v86, v2
	v_mul_f32_e32 v0, v0, v19
	v_cvt_pk_bf16_f32 v0, v0, s0
	ds_write_b16 v39, v0 offset:16592
	v_mul_f32_e32 v0, v86, v5
	v_mul_f32_e32 v0, v0, v20
	v_cvt_pk_bf16_f32 v0, v0, s0
	v_bfe_u32 v4, v38, 4, 2
	ds_write_b16 v88, v0 offset:16864
	v_mul_f32_e32 v0, v86, v3
	v_lshlrev_b32_e32 v2, 5, v4
	v_mov_b32_e32 v3, v1
	v_lshl_add_u64 v[8:9], s[6:7], 0, v[2:3]
	v_lshlrev_b32_e32 v2, 9, v67
	v_mul_f32_e32 v0, v0, v21
	v_lshl_or_b32 v16, v66, 14, v2
	v_mov_b32_e32 v17, v1
	v_cvt_pk_bf16_f32 v0, v0, s0
	v_lshl_add_u64 v[10:11], v[8:9], 0, v[16:17]
	ds_write_b16 v39, v0 offset:17136
	s_waitcnt lgkmcnt(0)
	s_barrier
; __device__ __forceinline__ void cmlp_item(const Params& p, int j, int rt, int g, const u16* __restrict__ ZB, u16* sVT) {
;     ...
;   const float* wsb = p.cmlp_ws + (size_t)(j * 4 + g) * 128 * 128;
; #pragma unroll
;   for (int ks = 0; ks < 4; ++ks) {
;     bf16x8 wf[2];
; #pragma unroll
;     for (int pb = 0; pb < 2; ++pb) {
;       const float* wp = wsb + (size_t)(wave * 32 + pb * 16 + fr) * 128 + ks * 32 + fq * 8;
;       float4 a = *(const float4*)wp, b = *(const float4*)(wp + 4);
;       wf[pb] = mk8(pack2(a.x, a.y), pack2(a.z, a.w), pack2(b.x, b.y), pack2(b.z, b.w));
;     }
; #pragma unroll
;     for (int db = 0; db < 8; ++db) {
;       bf16x8 vf = *(const bf16x8*)(sVT + (db * 16 + fr) * 136 + ks * 32 + fq * 8);
; #pragma unroll
;       for (int pb = 0; pb < 2; ++pb) acc[pb][db] = mfma16(vf, wf[pb], acc[pb][db]);
;     }
;   }
	v_or_b32_e32 v176, 0x2000, v16
	v_mov_b32_e32 v177, v1
	v_lshl_add_u64 v[176:177], v[8:9], 0, v[176:177]
	global_load_dwordx4 v[112:115], v[10:11], off offset:16
	global_load_dwordx4 v[116:119], v[10:11], off
	global_load_dwordx4 v[120:123], v[176:177], off offset:16
	global_load_dwordx4 v[124:127], v[176:177], off
	global_load_dwordx4 v[128:131], v[10:11], off offset:144
	global_load_dwordx4 v[132:135], v[10:11], off offset:128
	global_load_dwordx4 v[136:139], v[176:177], off offset:144
	global_load_dwordx4 v[140:143], v[176:177], off offset:128
	global_load_dwordx4 v[144:147], v[10:11], off offset:272
	global_load_dwordx4 v[148:151], v[10:11], off offset:256
	global_load_dwordx4 v[152:155], v[176:177], off offset:272
	global_load_dwordx4 v[156:159], v[176:177], off offset:256
	global_load_dwordx4 v[160:163], v[10:11], off offset:400
	global_load_dwordx4 v[164:167], v[10:11], off offset:384
	global_load_dwordx4 v[168:171], v[176:177], off offset:400
	global_load_dwordx4 v[172:175], v[176:177], off offset:384
	v_lshlrev_b32_e32 v0, 3, v4
	v_lshlrev_b32_e32 v18, 4, v4
	s_add_u32 s6, s92, s34
	s_addc_u32 s7, s93, 0
	s_add_i32 s8, s8, s87
	s_add_i32 s1, s1, s11
	s_add_i32 s0, s0, s86
	s_cmpk_gt_i32 s8, 0x47f
	s_waitcnt vmcnt(0)
	v_mov_b32_e32 v4, v112
	v_mov_b32_e32 v5, v113
	v_mov_b32_e32 v6, v114
	v_mov_b32_e32 v7, v115
	v_mov_b32_e32 v12, v116
	v_mov_b32_e32 v13, v117
	v_mov_b32_e32 v14, v118
	v_mov_b32_e32 v15, v119
	v_cvt_pk_bf16_f32 v4, v4, v5
	v_cvt_pk_bf16_f32 v5, v6, v7
	v_or_b32_e32 v6, 0x2000, v16
	v_mov_b32_e32 v7, v1
	s_waitcnt vmcnt(0)
	v_cvt_pk_bf16_f32 v2, v12, v13
	v_lshl_add_u64 v[12:13], v[8:9], 0, v[6:7]
	v_cvt_pk_bf16_f32 v3, v14, v15
	s_waitcnt vmcnt(0)
	v_mov_b32_e32 v14, v120
	v_mov_b32_e32 v15, v121
	v_mov_b32_e32 v16, v122
	v_mov_b32_e32 v17, v123
	v_mov_b32_e32 v6, v124
	v_mov_b32_e32 v7, v125
	v_mov_b32_e32 v8, v126
	v_mov_b32_e32 v9, v127
	v_cvt_pk_bf16_f32 v6, v6, v7
	v_cvt_pk_bf16_f32 v7, v8, v9
	v_cvt_pk_bf16_f32 v8, v14, v15
	v_mul_u32_u24_e32 v14, 0x88, v67
	v_lshlrev_b32_e32 v14, 1, v14
	v_add3_u32 v34, s58, v18, v14
	v_cvt_pk_bf16_f32 v9, v16, v17
	ds_read_b128 v[14:17], v34
	ds_read_b128 v[22:25], v34 offset:4352
	ds_read_b128 v[30:33], v34 offset:8704
	ds_read_b128 v[40:43], v34 offset:13056
	ds_read_b128 v[48:51], v34 offset:17408
	ds_read_b128 v[56:59], v34 offset:21760
	ds_read_b128 v[72:75], v34 offset:26112
	ds_read_b128 v[80:83], v34 offset:30464
	s_waitcnt lgkmcnt(7)
	v_mfma_f32_16x16x32_bf16 v[18:21], v[14:17], v[2:5], 0
	v_mfma_f32_16x16x32_bf16 v[14:17], v[14:17], v[6:9], 0
	s_waitcnt lgkmcnt(6)
	v_mfma_f32_16x16x32_bf16 v[26:29], v[22:25], v[2:5], 0
	v_mfma_f32_16x16x32_bf16 v[22:25], v[22:25], v[6:9], 0
	s_waitcnt lgkmcnt(5)
	v_mfma_f32_16x16x32_bf16 v[36:39], v[30:33], v[2:5], 0
	v_mfma_f32_16x16x32_bf16 v[30:33], v[30:33], v[6:9], 0
	s_waitcnt lgkmcnt(4)
	v_mfma_f32_16x16x32_bf16 v[44:47], v[40:43], v[2:5], 0
	v_mfma_f32_16x16x32_bf16 v[40:43], v[40:43], v[6:9], 0
	s_waitcnt lgkmcnt(3)
	v_mfma_f32_16x16x32_bf16 v[52:55], v[48:51], v[2:5], 0
	v_mfma_f32_16x16x32_bf16 v[48:51], v[48:51], v[6:9], 0
	s_waitcnt lgkmcnt(2)
	v_mfma_f32_16x16x32_bf16 v[60:63], v[56:59], v[2:5], 0
	v_mfma_f32_16x16x32_bf16 v[56:59], v[56:59], v[6:9], 0
	s_waitcnt lgkmcnt(1)
	v_mfma_f32_16x16x32_bf16 v[76:79], v[72:75], v[2:5], 0
	v_mfma_f32_16x16x32_bf16 v[72:75], v[72:75], v[6:9], 0
	s_waitcnt lgkmcnt(0)
	v_mfma_f32_16x16x32_bf16 v[2:5], v[80:83], v[2:5], 0
	v_mfma_f32_16x16x32_bf16 v[6:9], v[80:83], v[6:9], 0
	s_waitcnt vmcnt(0)
	v_mov_b32_e32 v80, v128
	v_mov_b32_e32 v81, v129
	v_mov_b32_e32 v82, v130
	v_mov_b32_e32 v83, v131
	v_mov_b32_e32 v84, v132
	v_mov_b32_e32 v85, v133
	v_mov_b32_e32 v86, v134
	v_mov_b32_e32 v87, v135
	v_cvt_pk_bf16_f32 v84, v84, v85
	v_cvt_pk_bf16_f32 v85, v86, v87
	v_cvt_pk_bf16_f32 v86, v80, v81
	v_cvt_pk_bf16_f32 v87, v82, v83
	s_waitcnt vmcnt(0)
	v_mov_b32_e32 v80, v136
	v_mov_b32_e32 v81, v137
	v_mov_b32_e32 v82, v138
	v_mov_b32_e32 v83, v139
	v_mov_b32_e32 v88, v140
	v_mov_b32_e32 v89, v141
	v_mov_b32_e32 v90, v142
	v_mov_b32_e32 v91, v143
	v_cvt_pk_bf16_f32 v88, v88, v89
	v_cvt_pk_bf16_f32 v89, v90, v91
	v_cvt_pk_bf16_f32 v90, v80, v81
	v_cvt_pk_bf16_f32 v91, v82, v83
	ds_read_b128 v[80:83], v34 offset:64
	s_waitcnt lgkmcnt(0)
	v_mfma_f32_16x16x32_bf16 v[18:21], v[80:83], v[84:87], v[18:21]
	v_mfma_f32_16x16x32_bf16 v[14:17], v[80:83], v[88:91], v[14:17]
	ds_read_b128 v[80:83], v34 offset:4416
	s_waitcnt lgkmcnt(0)
	v_mfma_f32_16x16x32_bf16 v[26:29], v[80:83], v[84:87], v[26:29]
	v_mfma_f32_16x16x32_bf16 v[22:25], v[80:83], v[88:91], v[22:25]
	ds_read_b128 v[80:83], v34 offset:8768
	s_waitcnt lgkmcnt(0)
	v_mfma_f32_16x16x32_bf16 v[36:39], v[80:83], v[84:87], v[36:39]
	v_mfma_f32_16x16x32_bf16 v[30:33], v[80:83], v[88:91], v[30:33]
	ds_read_b128 v[80:83], v34 offset:13120
	s_waitcnt lgkmcnt(0)
	v_mfma_f32_16x16x32_bf16 v[44:47], v[80:83], v[84:87], v[44:47]
	v_mfma_f32_16x16x32_bf16 v[40:43], v[80:83], v[88:91], v[40:43]
	ds_read_b128 v[80:83], v34 offset:17472
	s_waitcnt lgkmcnt(0)
	v_mfma_f32_16x16x32_bf16 v[52:55], v[80:83], v[84:87], v[52:55]
	v_mfma_f32_16x16x32_bf16 v[48:51], v[80:83], v[88:91], v[48:51]
	ds_read_b128 v[80:83], v34 offset:21824
	s_waitcnt lgkmcnt(0)
	v_mfma_f32_16x16x32_bf16 v[60:63], v[80:83], v[84:87], v[60:63]
	v_mfma_f32_16x16x32_bf16 v[56:59], v[80:83], v[88:91], v[56:59]
	ds_read_b128 v[80:83], v34 offset:26176
	s_waitcnt lgkmcnt(0)
	v_mfma_f32_16x16x32_bf16 v[76:79], v[80:83], v[84:87], v[76:79]
	v_mfma_f32_16x16x32_bf16 v[72:75], v[80:83], v[88:91], v[72:75]
	ds_read_b128 v[80:83], v34 offset:30528
	s_waitcnt lgkmcnt(0)
; __device__ __forceinline__ void cmlp_item(const Params& p, int j, int rt, int g, const u16* __restrict__ ZB, u16* sVT) {
;     ...
;   for (int ks = 0; ks < 4; ++ks) {
;     bf16x8 wf[2];
; #pragma unroll
;     for (int pb = 0; pb < 2; ++pb) {
;       const float* wp = wsb + (size_t)(wave * 32 + pb * 16 + fr) * 128 + ks * 32 + fq * 8;
;       float4 a = *(const float4*)wp, b = *(const float4*)(wp + 4);
;       wf[pb] = mk8(pack2(a.x, a.y), pack2(a.z, a.w), pack2(b.x, b.y), pack2(b.z, b.w));
;     }
; #pragma unroll
;     for (int db = 0; db < 8; ++db) {
;       bf16x8 vf = *(const bf16x8*)(sVT + (db * 16 + fr) * 136 + ks * 32 + fq * 8);
; #pragma unroll
;       for (int pb = 0; pb < 2; ++pb) acc[pb][db] = mfma16(vf, wf[pb], acc[pb][db]);
;     }
;   }
; #pragma unroll
;   for (int pb = 0; pb < 2; ++pb) {
;     const int pp = wave * 32 + pb * 16 + fr;
;     const float bias = p.cmlp_bs[(j * 4 + g) * 128 + pp];
; #pragma unroll
;     for (int db = 0; db < 8; ++db) {
;       const int d = db * 16 + fq * 4;
;       uint2 uu = *(const uint2*)(ZB + (size_t)(m0 + pp) * 1024 + g * 128 + d);
	v_mfma_f32_16x16x32_bf16 v[2:5], v[80:83], v[84:87], v[2:5]
	v_mfma_f32_16x16x32_bf16 v[6:9], v[80:83], v[88:91], v[6:9]
	s_waitcnt vmcnt(0)
	v_mov_b32_e32 v80, v144
	v_mov_b32_e32 v81, v145
	v_mov_b32_e32 v82, v146
	v_mov_b32_e32 v83, v147
	v_mov_b32_e32 v84, v148
	v_mov_b32_e32 v85, v149
	v_mov_b32_e32 v86, v150
	v_mov_b32_e32 v87, v151
	v_cvt_pk_bf16_f32 v84, v84, v85
	v_cvt_pk_bf16_f32 v85, v86, v87
	v_cvt_pk_bf16_f32 v86, v80, v81
	v_cvt_pk_bf16_f32 v87, v82, v83
	s_waitcnt vmcnt(0)
	v_mov_b32_e32 v80, v152
	v_mov_b32_e32 v81, v153
	v_mov_b32_e32 v82, v154
	v_mov_b32_e32 v83, v155
	v_mov_b32_e32 v88, v156
	v_mov_b32_e32 v89, v157
	v_mov_b32_e32 v90, v158
	v_mov_b32_e32 v91, v159
	v_cvt_pk_bf16_f32 v88, v88, v89
	v_cvt_pk_bf16_f32 v89, v90, v91
	v_cvt_pk_bf16_f32 v90, v80, v81
	v_cvt_pk_bf16_f32 v91, v82, v83
	ds_read_b128 v[80:83], v34 offset:128
	s_waitcnt lgkmcnt(0)
	v_mfma_f32_16x16x32_bf16 v[18:21], v[80:83], v[84:87], v[18:21]
	v_mfma_f32_16x16x32_bf16 v[14:17], v[80:83], v[88:91], v[14:17]
	ds_read_b128 v[80:83], v34 offset:4480
	s_waitcnt lgkmcnt(0)
	v_mfma_f32_16x16x32_bf16 v[26:29], v[80:83], v[84:87], v[26:29]
	v_mfma_f32_16x16x32_bf16 v[22:25], v[80:83], v[88:91], v[22:25]
	ds_read_b128 v[80:83], v34 offset:8832
	s_waitcnt lgkmcnt(0)
	v_mfma_f32_16x16x32_bf16 v[36:39], v[80:83], v[84:87], v[36:39]
	v_mfma_f32_16x16x32_bf16 v[80:83], v[80:83], v[88:91], v[30:33]
	s_nop 2
	ds_read_b128 v[30:33], v34 offset:13184
	s_waitcnt lgkmcnt(0)
	v_mfma_f32_16x16x32_bf16 v[44:47], v[30:33], v[84:87], v[44:47]
	v_mfma_f32_16x16x32_bf16 v[40:43], v[30:33], v[88:91], v[40:43]
	ds_read_b128 v[30:33], v34 offset:17536
	s_waitcnt lgkmcnt(0)
	v_mfma_f32_16x16x32_bf16 v[92:95], v[30:33], v[84:87], v[52:55]
	v_mfma_f32_16x16x32_bf16 v[96:99], v[30:33], v[88:91], v[48:51]
	ds_read_b128 v[30:33], v34 offset:21888
	s_waitcnt lgkmcnt(0)
	v_mfma_f32_16x16x32_bf16 v[100:103], v[30:33], v[84:87], v[60:63]
	v_mfma_f32_16x16x32_bf16 v[104:107], v[30:33], v[88:91], v[56:59]
	ds_read_b128 v[30:33], v34 offset:26240
	s_waitcnt lgkmcnt(0)
	v_mfma_f32_16x16x32_bf16 v[76:79], v[30:33], v[84:87], v[76:79]
	v_mfma_f32_16x16x32_bf16 v[72:75], v[30:33], v[88:91], v[72:75]
	ds_read_b128 v[30:33], v34 offset:30592
	s_waitcnt lgkmcnt(0)
	v_mfma_f32_16x16x32_bf16 v[2:5], v[30:33], v[84:87], v[2:5]
	v_mfma_f32_16x16x32_bf16 v[84:87], v[30:33], v[88:91], v[6:9]
	s_nop 2
	s_waitcnt vmcnt(0)
	v_mov_b32_e32 v6, v160
	v_mov_b32_e32 v7, v161
	v_mov_b32_e32 v8, v162
	v_mov_b32_e32 v9, v163
	v_mov_b32_e32 v30, v164
	v_mov_b32_e32 v31, v165
	v_mov_b32_e32 v32, v166
	v_mov_b32_e32 v33, v167
	v_cvt_pk_bf16_f32 v90, v6, v7
	v_cvt_pk_bf16_f32 v91, v8, v9
	s_nop 0
	s_waitcnt vmcnt(0)
	v_mov_b32_e32 v6, v168
	v_mov_b32_e32 v7, v169
	v_mov_b32_e32 v8, v170
	v_mov_b32_e32 v9, v171
	v_mov_b32_e32 v10, v172
	v_mov_b32_e32 v11, v173
	v_mov_b32_e32 v12, v174
	v_mov_b32_e32 v13, v175
	v_cvt_pk_bf16_f32 v88, v30, v31
	v_cvt_pk_bf16_f32 v89, v32, v33
	s_waitcnt vmcnt(0)
	v_cvt_pk_bf16_f32 v110, v6, v7
	v_cvt_pk_bf16_f32 v111, v8, v9
	ds_read_b128 v[6:9], v34 offset:192
	s_waitcnt vmcnt(0)
	v_cvt_pk_bf16_f32 v108, v10, v11
	v_cvt_pk_bf16_f32 v109, v12, v13
	s_waitcnt lgkmcnt(0)
	v_mfma_f32_16x16x32_bf16 v[62:65], v[6:9], v[88:91], v[18:21]
	v_mfma_f32_16x16x32_bf16 v[30:33], v[6:9], v[108:111], v[14:17]
	ds_read_b128 v[6:9], v34 offset:4544
	s_waitcnt lgkmcnt(0)
	v_mfma_f32_16x16x32_bf16 v[58:61], v[6:9], v[88:91], v[26:29]
	v_mfma_f32_16x16x32_bf16 v[26:29], v[6:9], v[108:111], v[22:25]
	ds_read_b128 v[6:9], v34 offset:8896
	s_waitcnt lgkmcnt(0)
	v_mfma_f32_16x16x32_bf16 v[54:57], v[6:9], v[88:91], v[36:39]
	v_mfma_f32_16x16x32_bf16 v[22:25], v[6:9], v[108:111], v[80:83]
	ds_read_b128 v[6:9], v34 offset:13248
	s_waitcnt lgkmcnt(0)
	v_mfma_f32_16x16x32_bf16 v[50:53], v[6:9], v[88:91], v[44:47]
	v_mfma_f32_16x16x32_bf16 v[18:21], v[6:9], v[108:111], v[40:43]
	ds_read_b128 v[6:9], v34 offset:17600
	s_waitcnt lgkmcnt(0)
	v_mfma_f32_16x16x32_bf16 v[46:49], v[6:9], v[88:91], v[92:95]
	v_mfma_f32_16x16x32_bf16 v[14:17], v[6:9], v[108:111], v[96:99]
	ds_read_b128 v[6:9], v34 offset:21952
	s_waitcnt lgkmcnt(0)
	v_mfma_f32_16x16x32_bf16 v[42:45], v[6:9], v[88:91], v[100:103]
	v_mfma_f32_16x16x32_bf16 v[10:13], v[6:9], v[108:111], v[104:107]
	ds_read_b128 v[6:9], v34 offset:26304
	s_waitcnt lgkmcnt(0)
	v_mfma_f32_16x16x32_bf16 v[38:41], v[6:9], v[88:91], v[76:79]
	v_mfma_f32_16x16x32_bf16 v[6:9], v[6:9], v[108:111], v[72:75]
	s_nop 2
	ds_read_b128 v[72:75], v34 offset:30656
	s_waitcnt lgkmcnt(0)
	v_mfma_f32_16x16x32_bf16 v[34:37], v[72:75], v[88:91], v[2:5]
	v_mfma_f32_16x16x32_bf16 v[2:5], v[72:75], v[108:111], v[84:87]
	v_lshl_or_b32 v72, v66, 5, v67
	v_lshl_or_b32 v66, s10, 7, v72
	v_mov_b32_e32 v67, v1
	v_lshl_add_u64 v[68:69], v[66:67], 2, s[48:49]
	v_or_b32_e32 v66, s9, v72
	v_ashrrev_i32_e32 v67, 31, v66
	v_lshlrev_b64 v[76:77], 11, v[66:67]
	v_lshl_add_u64 v[72:73], s[6:7], 0, v[76:77]
	v_lshl_add_u64 v[72:73], v[72:73], 0, v[0:1]
	global_load_dword v70, v[68:69], off
	global_load_dwordx2 v[78:79], v[72:73], off
	global_load_dword v112, v[68:69], off offset:64
	global_load_dwordx2 v[114:115], v[72:73], off offset:32
	global_load_dwordx2 v[116:117], v[72:73], off offset:64
	global_load_dwordx2 v[118:119], v[72:73], off offset:96
	global_load_dwordx2 v[120:121], v[72:73], off offset:128
	global_load_dwordx2 v[122:123], v[72:73], off offset:160
	global_load_dwordx2 v[124:125], v[72:73], off offset:192
	global_load_dwordx2 v[126:127], v[72:73], off offset:224
	v_or_b32_e32 v144, 16, v66
	v_ashrrev_i32_e32 v145, 31, v144
	v_lshlrev_b64 v[144:145], 11, v[144:145]
	v_lshl_add_u64 v[144:145], s[6:7], 0, v[144:145]
	v_lshl_add_u64 v[144:145], v[144:145], 0, v[0:1]
	global_load_dwordx2 v[128:129], v[144:145], off
	global_load_dwordx2 v[130:131], v[144:145], off offset:32
	global_load_dwordx2 v[132:133], v[144:145], off offset:64
	global_load_dwordx2 v[134:135], v[144:145], off offset:96
	global_load_dwordx2 v[136:137], v[144:145], off offset:128
	global_load_dwordx2 v[138:139], v[144:145], off offset:160
	global_load_dwordx2 v[140:141], v[144:145], off offset:192
	global_load_dwordx2 v[142:143], v[144:145], off offset:224
	s_waitcnt vmcnt(0)
; __device__ __forceinline__ float lo_bf(unsigned u) { return __uint_as_float(u << 16); }
; __device__ __forceinline__ float hi_bf(unsigned u) { return __uint_as_float(u & 0xffff0000u); }
; __device__ __forceinline__ void cmlp_item(const Params& p, int j, int rt, int g, const u16* __restrict__ ZB, u16* sVT) {
;     ...
; #pragma unroll
;   for (int pb = 0; pb < 2; ++pb) {
;     const int pp = wave * 32 + pb * 16 + fr;
;     const float bias = p.cmlp_bs[(j * 4 + g) * 128 + pp];
; #pragma unroll
;     for (int db = 0; db < 8; ++db) {
;       const int d = db * 16 + fq * 4;
;       uint2 uu = *(const uint2*)(ZB + (size_t)(m0 + pp) * 1024 + g * 128 + d);
;       f32x4 r;
;       r[0] = lo_bf(uu.x) * (acc[pb][db][0] + bias);
;       r[1] = hi_bf(uu.x) * (acc[pb][db][1] + bias);
;       r[2] = lo_bf(uu.y) * (acc[pb][db][2] + bias);
;       r[3] = hi_bf(uu.y) * (acc[pb][db][3] + bias);
;       store4bf(p.XN + (size_t)(m0 + pp) * 1024 + 512 + g * 128 + d, r);
;     }
;   }
	v_pk_add_f32 v[62:63], v[62:63], v[70:71] op_sel_hi:[1,0]
	v_lshlrev_b32_e32 v74, 16, v78
	v_and_b32_e32 v75, 0xffff0000, v78
	v_pk_mul_f32 v[74:75], v[62:63], v[74:75]
	v_lshlrev_b32_e32 v62, 16, v79
	v_and_b32_e32 v63, 0xffff0000, v79
	v_pk_add_f32 v[64:65], v[64:65], v[70:71] op_sel_hi:[1,0]
	v_cvt_pk_bf16_f32 v74, v74, v75
	v_pk_mul_f32 v[64:65], v[64:65], v[62:63]
	v_lshl_add_u64 v[62:63], s[42:43], 0, v[76:77]
	v_lshl_add_u64 v[62:63], v[62:63], 0, s[34:35]
	v_lshl_add_u64 v[62:63], v[62:63], 0, v[0:1]
	v_cvt_pk_bf16_f32 v75, v64, v65
	global_store_dwordx2 v[62:63], v[74:75], off offset:1024
	v_mov_b32_e32 v64, v114
	v_mov_b32_e32 v65, v115
	v_pk_add_f32 v[58:59], v[58:59], v[70:71] op_sel_hi:[1,0]
	v_pk_add_f32 v[60:61], v[60:61], v[70:71] op_sel_hi:[1,0]
	v_pk_add_f32 v[54:55], v[54:55], v[70:71] op_sel_hi:[1,0]
	v_pk_add_f32 v[56:57], v[56:57], v[70:71] op_sel_hi:[1,0]
	v_pk_add_f32 v[50:51], v[50:51], v[70:71] op_sel_hi:[1,0]
	v_pk_add_f32 v[52:53], v[52:53], v[70:71] op_sel_hi:[1,0]
	v_pk_add_f32 v[46:47], v[46:47], v[70:71] op_sel_hi:[1,0]
	v_pk_add_f32 v[48:49], v[48:49], v[70:71] op_sel_hi:[1,0]
	v_pk_add_f32 v[42:43], v[42:43], v[70:71] op_sel_hi:[1,0]
	v_pk_add_f32 v[44:45], v[44:45], v[70:71] op_sel_hi:[1,0]
	v_pk_add_f32 v[38:39], v[38:39], v[70:71] op_sel_hi:[1,0]
	v_pk_add_f32 v[40:41], v[40:41], v[70:71] op_sel_hi:[1,0]
	v_pk_add_f32 v[34:35], v[34:35], v[70:71] op_sel_hi:[1,0]
	v_pk_add_f32 v[36:37], v[36:37], v[70:71] op_sel_hi:[1,0]
	v_lshlrev_b32_e32 v74, 16, v64
	v_and_b32_e32 v75, 0xffff0000, v64
	v_lshlrev_b32_e32 v64, 16, v65
	v_and_b32_e32 v65, 0xffff0000, v65
	v_pk_mul_f32 v[58:59], v[58:59], v[74:75]
	v_pk_mul_f32 v[60:61], v[60:61], v[64:65]
	v_cvt_pk_bf16_f32 v58, v58, v59
	v_cvt_pk_bf16_f32 v59, v60, v61
	global_store_dwordx2 v[62:63], v[58:59], off offset:1056
	v_mov_b32_e32 v58, v116
	v_mov_b32_e32 v59, v117
	v_lshlrev_b32_e32 v60, 16, v58
	v_and_b32_e32 v61, 0xffff0000, v58
	v_lshlrev_b32_e32 v58, 16, v59
	v_and_b32_e32 v59, 0xffff0000, v59
	v_pk_mul_f32 v[54:55], v[54:55], v[60:61]
	v_pk_mul_f32 v[56:57], v[56:57], v[58:59]
	v_cvt_pk_bf16_f32 v54, v54, v55
	v_cvt_pk_bf16_f32 v55, v56, v57
	global_store_dwordx2 v[62:63], v[54:55], off offset:1088
	v_mov_b32_e32 v54, v118
	v_mov_b32_e32 v55, v119
	v_lshlrev_b32_e32 v56, 16, v54
	v_and_b32_e32 v57, 0xffff0000, v54
	v_lshlrev_b32_e32 v54, 16, v55
	v_and_b32_e32 v55, 0xffff0000, v55
	v_pk_mul_f32 v[50:51], v[50:51], v[56:57]
	v_pk_mul_f32 v[52:53], v[52:53], v[54:55]
	v_cvt_pk_bf16_f32 v50, v50, v51
	v_cvt_pk_bf16_f32 v51, v52, v53
	global_store_dwordx2 v[62:63], v[50:51], off offset:1120
	v_mov_b32_e32 v50, v120
	v_mov_b32_e32 v51, v121
	v_lshlrev_b32_e32 v52, 16, v50
	v_and_b32_e32 v53, 0xffff0000, v50
	v_lshlrev_b32_e32 v50, 16, v51
	v_and_b32_e32 v51, 0xffff0000, v51
	v_pk_mul_f32 v[46:47], v[46:47], v[52:53]
	v_pk_mul_f32 v[48:49], v[48:49], v[50:51]
	v_cvt_pk_bf16_f32 v46, v46, v47
	v_cvt_pk_bf16_f32 v47, v48, v49
	global_store_dwordx2 v[62:63], v[46:47], off offset:1152
	v_mov_b32_e32 v46, v122
	v_mov_b32_e32 v47, v123
	v_lshlrev_b32_e32 v48, 16, v46
	v_and_b32_e32 v49, 0xffff0000, v46
	v_lshlrev_b32_e32 v46, 16, v47
	v_and_b32_e32 v47, 0xffff0000, v47
	v_pk_mul_f32 v[42:43], v[42:43], v[48:49]
	v_pk_mul_f32 v[44:45], v[44:45], v[46:47]
	v_cvt_pk_bf16_f32 v42, v42, v43
	v_cvt_pk_bf16_f32 v43, v44, v45
	global_store_dwordx2 v[62:63], v[42:43], off offset:1184
	v_mov_b32_e32 v42, v124
	v_mov_b32_e32 v43, v125
	v_lshlrev_b32_e32 v44, 16, v42
	v_and_b32_e32 v45, 0xffff0000, v42
	v_lshlrev_b32_e32 v42, 16, v43
	v_and_b32_e32 v43, 0xffff0000, v43
	v_pk_mul_f32 v[38:39], v[38:39], v[44:45]
	v_pk_mul_f32 v[40:41], v[40:41], v[42:43]
	v_cvt_pk_bf16_f32 v38, v38, v39
	v_cvt_pk_bf16_f32 v39, v40, v41
	global_store_dwordx2 v[62:63], v[38:39], off offset:1216
	v_mov_b32_e32 v38, v126
	v_mov_b32_e32 v39, v127
	v_lshlrev_b32_e32 v40, 16, v38
	v_and_b32_e32 v41, 0xffff0000, v38
	v_lshlrev_b32_e32 v38, 16, v39
	v_and_b32_e32 v39, 0xffff0000, v39
	v_pk_mul_f32 v[34:35], v[34:35], v[40:41]
	v_pk_mul_f32 v[36:37], v[36:37], v[38:39]
	v_cvt_pk_bf16_f32 v34, v34, v35
	v_cvt_pk_bf16_f32 v35, v36, v37
	v_or_b32_e32 v36, 16, v66
	v_ashrrev_i32_e32 v37, 31, v36
	v_lshlrev_b64 v[38:39], 11, v[36:37]
	v_lshl_add_u64 v[36:37], s[6:7], 0, v[38:39]
	global_store_dwordx2 v[62:63], v[34:35], off offset:1248
; __device__ __forceinline__ float lo_bf(unsigned u) { return __uint_as_float(u << 16); }
; __device__ __forceinline__ float hi_bf(unsigned u) { return __uint_as_float(u & 0xffff0000u); }
; __device__ __forceinline__ void cmlp_item(const Params& p, int j, int rt, int g, const u16* __restrict__ ZB, u16* sVT) {
;     ...
; #pragma unroll
;   for (int pb = 0; pb < 2; ++pb) {
;     const int pp = wave * 32 + pb * 16 + fr;
;     const float bias = p.cmlp_bs[(j * 4 + g) * 128 + pp];
; #pragma unroll
;     for (int db = 0; db < 8; ++db) {
;       const int d = db * 16 + fq * 4;
;       uint2 uu = *(const uint2*)(ZB + (size_t)(m0 + pp) * 1024 + g * 128 + d);
;       f32x4 r;
;       r[0] = lo_bf(uu.x) * (acc[pb][db][0] + bias);
;       r[1] = hi_bf(uu.x) * (acc[pb][db][1] + bias);
;       r[2] = lo_bf(uu.y) * (acc[pb][db][2] + bias);
;       r[3] = hi_bf(uu.y) * (acc[pb][db][3] + bias);
;       store4bf(p.XN + (size_t)(m0 + pp) * 1024 + 512 + g * 128 + d, r);
;     }
;   }
	v_lshl_add_u64 v[36:37], v[36:37], 0, v[0:1]
	v_mov_b32_e32 v34, v112
	v_mov_b32_e32 v40, v128
	v_mov_b32_e32 v41, v129
	v_pk_add_f32 v[30:31], v[30:31], v[34:35] op_sel_hi:[1,0]
	v_lshlrev_b32_e32 v42, 16, v40
	v_and_b32_e32 v43, 0xffff0000, v40
	v_pk_mul_f32 v[42:43], v[30:31], v[42:43]
	v_lshlrev_b32_e32 v30, 16, v41
	v_and_b32_e32 v31, 0xffff0000, v41
	v_pk_add_f32 v[32:33], v[32:33], v[34:35] op_sel_hi:[1,0]
	v_pk_add_f32 v[26:27], v[26:27], v[34:35] op_sel_hi:[1,0]
	v_pk_mul_f32 v[32:33], v[32:33], v[30:31]
	v_lshl_add_u64 v[30:31], s[42:43], 0, v[38:39]
	v_lshl_add_u64 v[30:31], v[30:31], 0, s[34:35]
	v_lshl_add_u64 v[30:31], v[30:31], 0, v[0:1]
	v_cvt_pk_bf16_f32 v38, v42, v43
	v_cvt_pk_bf16_f32 v39, v32, v33
	global_store_dwordx2 v[30:31], v[38:39], off offset:1024
	v_mov_b32_e32 v32, v130
	v_mov_b32_e32 v33, v131
	v_pk_add_f32 v[28:29], v[28:29], v[34:35] op_sel_hi:[1,0]
	v_pk_add_f32 v[22:23], v[22:23], v[34:35] op_sel_hi:[1,0]
	v_pk_add_f32 v[24:25], v[24:25], v[34:35] op_sel_hi:[1,0]
	v_pk_add_f32 v[18:19], v[18:19], v[34:35] op_sel_hi:[1,0]
	v_pk_add_f32 v[20:21], v[20:21], v[34:35] op_sel_hi:[1,0]
	v_pk_add_f32 v[14:15], v[14:15], v[34:35] op_sel_hi:[1,0]
	v_pk_add_f32 v[16:17], v[16:17], v[34:35] op_sel_hi:[1,0]
	v_pk_add_f32 v[10:11], v[10:11], v[34:35] op_sel_hi:[1,0]
	v_pk_add_f32 v[12:13], v[12:13], v[34:35] op_sel_hi:[1,0]
	v_pk_add_f32 v[6:7], v[6:7], v[34:35] op_sel_hi:[1,0]
	v_pk_add_f32 v[8:9], v[8:9], v[34:35] op_sel_hi:[1,0]
	v_pk_add_f32 v[2:3], v[2:3], v[34:35] op_sel_hi:[1,0]
	v_pk_add_f32 v[4:5], v[4:5], v[34:35] op_sel_hi:[1,0]
	v_lshlrev_b32_e32 v38, 16, v32
	v_and_b32_e32 v39, 0xffff0000, v32
	v_lshlrev_b32_e32 v32, 16, v33
	v_and_b32_e32 v33, 0xffff0000, v33
	v_pk_mul_f32 v[26:27], v[26:27], v[38:39]
	v_pk_mul_f32 v[28:29], v[28:29], v[32:33]
	v_cvt_pk_bf16_f32 v26, v26, v27
	v_cvt_pk_bf16_f32 v27, v28, v29
	global_store_dwordx2 v[30:31], v[26:27], off offset:1056
	v_mov_b32_e32 v26, v132
	v_mov_b32_e32 v27, v133
	v_lshlrev_b32_e32 v28, 16, v26
	v_and_b32_e32 v29, 0xffff0000, v26
	v_lshlrev_b32_e32 v26, 16, v27
	v_and_b32_e32 v27, 0xffff0000, v27
	v_pk_mul_f32 v[22:23], v[22:23], v[28:29]
	v_pk_mul_f32 v[24:25], v[24:25], v[26:27]
	v_cvt_pk_bf16_f32 v22, v22, v23
	v_cvt_pk_bf16_f32 v23, v24, v25
	global_store_dwordx2 v[30:31], v[22:23], off offset:1088
	v_mov_b32_e32 v22, v134
	v_mov_b32_e32 v23, v135
	v_lshlrev_b32_e32 v24, 16, v22
	v_and_b32_e32 v25, 0xffff0000, v22
	v_lshlrev_b32_e32 v22, 16, v23
	v_and_b32_e32 v23, 0xffff0000, v23
	v_pk_mul_f32 v[18:19], v[18:19], v[24:25]
	v_pk_mul_f32 v[20:21], v[20:21], v[22:23]
	v_cvt_pk_bf16_f32 v18, v18, v19
	v_cvt_pk_bf16_f32 v19, v20, v21
	global_store_dwordx2 v[30:31], v[18:19], off offset:1120
	v_mov_b32_e32 v18, v136
	v_mov_b32_e32 v19, v137
	v_lshlrev_b32_e32 v20, 16, v18
	v_and_b32_e32 v21, 0xffff0000, v18
	v_lshlrev_b32_e32 v18, 16, v19
	v_and_b32_e32 v19, 0xffff0000, v19
	v_pk_mul_f32 v[14:15], v[14:15], v[20:21]
	v_pk_mul_f32 v[16:17], v[16:17], v[18:19]
	v_cvt_pk_bf16_f32 v14, v14, v15
	v_cvt_pk_bf16_f32 v15, v16, v17
	global_store_dwordx2 v[30:31], v[14:15], off offset:1152
	v_mov_b32_e32 v14, v138
	v_mov_b32_e32 v15, v139
	v_lshlrev_b32_e32 v16, 16, v14
	v_and_b32_e32 v17, 0xffff0000, v14
	v_lshlrev_b32_e32 v14, 16, v15
	v_and_b32_e32 v15, 0xffff0000, v15
	v_pk_mul_f32 v[10:11], v[10:11], v[16:17]
	v_pk_mul_f32 v[12:13], v[12:13], v[14:15]
	v_cvt_pk_bf16_f32 v10, v10, v11
	v_cvt_pk_bf16_f32 v11, v12, v13
	global_store_dwordx2 v[30:31], v[10:11], off offset:1184
	v_mov_b32_e32 v10, v140
	v_mov_b32_e32 v11, v141
	v_lshlrev_b32_e32 v12, 16, v10
	v_and_b32_e32 v13, 0xffff0000, v10
	v_lshlrev_b32_e32 v10, 16, v11
	v_and_b32_e32 v11, 0xffff0000, v11
	v_pk_mul_f32 v[6:7], v[6:7], v[12:13]
	v_pk_mul_f32 v[8:9], v[8:9], v[10:11]
	v_cvt_pk_bf16_f32 v6, v6, v7
	v_cvt_pk_bf16_f32 v7, v8, v9
	global_store_dwordx2 v[30:31], v[6:7], off offset:1216
	v_mov_b32_e32 v6, v142
	v_mov_b32_e32 v7, v143
	v_lshlrev_b32_e32 v8, 16, v6
	v_and_b32_e32 v9, 0xffff0000, v6
	v_lshlrev_b32_e32 v6, 16, v7
	v_and_b32_e32 v7, 0xffff0000, v7
	v_pk_mul_f32 v[2:3], v[2:3], v[8:9]
	v_pk_mul_f32 v[4:5], v[4:5], v[6:7]
	v_cvt_pk_bf16_f32 v2, v2, v3
	v_cvt_pk_bf16_f32 v3, v4, v5
	global_store_dwordx2 v[30:31], v[2:3], off offset:1248
	s_cbranch_scc0 .LBB0_1553
	v_readlane_b32 s44, v255, 21
	s_branch .LBB0_1524
